# P6 gate-merge epilogue: gate and dst pieces fetched two groups ahead into dead operand registers, counted vmcnt waits instead of vmcnt(0) per piece
# speedup vs baseline: 1.0048x; 1.0048x over previous
; __device__ __forceinline__ float sigm(float x) { return 1.f / (1.f + __expf(-x)); }
;     __device__ __forceinline__ void operator()(const pg8::f32x4 (&acc)[2][2][4][2], const pg8::Unit& u, int wr, int wc, int fr, int fq) const {
;     ...
; #pragma unroll
;             for (int ai = 0; ai < 2; ++ai)
; #pragma unroll
;                 for (int m = 0; m < 4; ++m) {
;                     const int row = rowb + ai * 128 + m * 16;
;                     const float rsv = rs8[ai][m];
;                     float sacc = 0.f;
; #pragma unroll
;                     for (int bj = 0; bj < 2; ++bj) {
;                         float o[8];
; #pragma unroll
;                         for (int n = 0; n < 2; ++n)
; #pragma unroll
;                             for (int j = 0; j < 4; ++j) o[4 * n + j] = acc[ai][bj][m][n][j] * rsv;
;                         if (sig) {
; #pragma unroll
;                             for (int e = 0; e < 8; ++e) o[e] = sigm(o[e]);
;                             if (mode == EM_Z2) { const f32x4 h0 = *(const f32x4*)(gain0 + colb - 2048 + bj * 128 + cl), h1_ = *(const f32x4*)(gain0 + colb - 2048 + bj * 128 + cl + 4);
; #pragma unroll
;                                 for (int e = 0; e < 4; ++e) { o[e] *= h0[e]; o[4 + e] *= h1_[e]; } }
;                         }
;                         if (gt) { float gv[8]; unpack8(*(const u32x4*)(gt + (size_t)row * Z2_LD + gcol + bj * 128 + cl), gv);
; #pragma unroll
;                             for (int e = 0; e < 8; ++e) o[e] *= gv[e]; }
;                         bf16_t* p = dst + (size_t)row * ldc + colb + bj * 128 + cl;
;                         if (addt) { float tv[8]; unpack8(*(const u32x4*)p, tv);
; #pragma unroll
;                             for (int e = 0; e < 8; ++e) o[e] += tv[e]; }
.LBB0_350:
	s_xor_b64 s[18:19], s[54:55], -1
	v_add_u32_e32 v180, 0x80, v178
	s_andn2_b64 vcc, exec, s[18:19]
	s_mov_b64 s[18:19], -1
	s_cbranch_vccnz .LBB0_584
	s_cmp_eq_u64 s[72:73], 0
	s_cbranch_scc1 .Lgq_skip
	v_add_u32_e32 v246, s46, v156
	v_lshlrev_b32_e32 v246, 1, v246
	v_mov_b32_e32 v247, 0
	v_lshlrev_b64 v[250:251], 13, v[178:179]
	v_lshl_add_u64 v[246:247], v[246:247], 0, s[72:73]
	v_lshl_add_u64 v[246:247], v[246:247], 0, v[250:251]
	global_load_dwordx4 v[234:237], v[246:247], off
	global_load_dwordx4 v[238:241], v[246:247], off offset:256
	v_mov_b32_e32 v250, 0x10000
	v_mov_b32_e32 v251, 0
	s_cmp_eq_u64 s[48:49], 0
	s_cbranch_scc1 .Lgq_skip
	v_add_u32_e32 v248, s86, v156
	v_lshlrev_b32_e32 v248, 1, v248
	v_mov_b32_e32 v249, 0
	v_lshlrev_b64 v[226:227], 12, v[178:179]
	v_lshl_add_u64 v[248:249], v[248:249], 0, s[14:15]
	v_lshl_add_u64 v[248:249], v[248:249], 0, v[226:227]
	global_load_dwordx4 v[242:245], v[248:249], off
	global_load_dwordx4 v[222:225], v[248:249], off offset:256
.Lgq_skip:
	s_ashr_i32 s87, s86, 31
	s_lshl_b64 s[18:19], s[86:87], 2
	s_add_u32 s18, s68, s18
	s_addc_u32 s19, s69, s19
	v_lshlrev_b32_e32 v0, 2, v156
	v_lshl_add_u64 v[130:131], s[18:19], 0, v[0:1]
	s_movk_i32 s18, 0xe000
	s_mov_b32 s19, -1
	v_cndmask_b32_e64 v0, 0, 1, s[22:23]
	v_lshl_add_u64 v[134:135], v[130:131], 0, s[18:19]
	v_pk_mul_f32 v[140:141], v[126:127], v[176:177] op_sel_hi:[1,0]
	v_pk_mul_f32 v[182:183], v[128:129], v[176:177] op_sel_hi:[1,0]
	v_pk_mul_f32 v[144:145], v[122:123], v[176:177] op_sel_hi:[1,0]
	v_pk_mul_f32 v[142:143], v[124:125], v[176:177] op_sel_hi:[1,0]
	s_and_b64 vcc, exec, s[50:51]
	v_cmp_ne_u32_e64 s[44:45], 1, v0
	s_cbranch_vccz .LBB0_354
	v_mul_f32_e32 v0, 0xbfb8aa3b, v140
	v_exp_f32_e32 v130, v0
	v_mul_f32_e32 v0, 0xbfb8aa3b, v141
	v_exp_f32_e32 v131, v0
	s_nop 0
	v_pk_add_f32 v[130:131], v[130:131], 1.0 op_sel_hi:[1,0]
	s_nop 0
	s_nop 0
	v_rcp_f32_e32 v141, v131
	s_nop 0
	s_nop 0
	v_rcp_f32_e32 v140, v130
	s_nop 0
	v_mul_f32_e32 v0, 0xbfb8aa3b, v182
	v_exp_f32_e32 v130, v0
	v_mul_f32_e32 v0, 0xbfb8aa3b, v183
	v_exp_f32_e32 v131, v0
	s_nop 0
	v_pk_add_f32 v[130:131], v[130:131], 1.0 op_sel_hi:[1,0]
	s_nop 0
	s_nop 0
	v_rcp_f32_e32 v183, v131
	s_nop 0
	s_nop 0
	v_rcp_f32_e32 v182, v130
	s_nop 0
	v_mul_f32_e32 v0, 0xbfb8aa3b, v144
	v_exp_f32_e32 v130, v0
	v_mul_f32_e32 v0, 0xbfb8aa3b, v145
	v_exp_f32_e32 v131, v0
	s_nop 0
	v_pk_add_f32 v[130:131], v[130:131], 1.0 op_sel_hi:[1,0]
	s_nop 0
	s_nop 0
	v_rcp_f32_e32 v145, v131
	s_nop 0
	s_nop 0
	v_rcp_f32_e32 v144, v130
	s_nop 0
	v_mul_f32_e32 v0, 0xbfb8aa3b, v142
	v_exp_f32_e32 v130, v0
	v_mul_f32_e32 v0, 0xbfb8aa3b, v143
	v_exp_f32_e32 v131, v0
	s_nop 0
	v_pk_add_f32 v[130:131], v[130:131], 1.0 op_sel_hi:[1,0]
	s_nop 0
	s_nop 0
	v_rcp_f32_e32 v143, v131
	s_nop 0
	s_nop 0
	v_rcp_f32_e32 v142, v130
	s_nop 0
	s_and_b64 vcc, exec, s[44:45]
	s_cbranch_vccnz .LBB0_354
	global_load_dwordx4 v[130:133], v[134:135], off
	global_load_dwordx4 v[136:139], v[134:135], off offset:16
	s_waitcnt vmcnt(1)
	v_pk_mul_f32 v[182:183], v[182:183], v[132:133]
	v_pk_mul_f32 v[140:141], v[140:141], v[130:131]
	s_waitcnt vmcnt(0)
	v_pk_mul_f32 v[142:143], v[142:143], v[138:139]
	v_pk_mul_f32 v[144:145], v[144:145], v[136:137]
.LBB0_354:
	s_waitcnt lgkmcnt(0)
	s_cmp_lg_u64 s[72:73], 0
	s_cselect_b64 s[52:53], -1, 0
	s_ashr_i32 s47, s46, 31
	s_lshl_b64 s[18:19], s[46:47], 1
	s_add_u32 s18, s72, s18
	s_addc_u32 s19, s73, s19
	v_lshlrev_b32_e32 v0, 1, v156
	v_lshl_add_u64 v[136:137], s[18:19], 0, v[0:1]
	v_lshlrev_b64 v[130:131], 13, v[178:179]
	s_cmp_eq_u64 s[72:73], 0
	v_lshl_add_u64 v[194:195], v[136:137], 0, v[130:131]
	s_cbranch_scc1 .LBB0_356
	s_waitcnt vmcnt(1)
	v_mov_b32_e32 v130, v234
	v_mov_b32_e32 v131, v235
	v_mov_b32_e32 v132, v236
	v_mov_b32_e32 v133, v237
	v_lshl_add_u64 v[246:247], v[250:251], 1, v[246:247]
	global_load_dwordx4 v[234:237], v[246:247], off
	v_lshlrev_b32_e32 v138, 16, v130
	v_and_b32_e32 v139, 0xffff0000, v130
	v_lshlrev_b32_e32 v130, 16, v131
	v_and_b32_e32 v131, 0xffff0000, v131
	v_pk_mul_f32 v[182:183], v[182:183], v[130:131]
	v_lshlrev_b32_e32 v130, 16, v132
	v_and_b32_e32 v131, 0xffff0000, v132
	v_pk_mul_f32 v[144:145], v[144:145], v[130:131]
	v_lshlrev_b32_e32 v130, 16, v133
	v_and_b32_e32 v131, 0xffff0000, v133
	v_pk_mul_f32 v[140:141], v[140:141], v[138:139]
	v_pk_mul_f32 v[142:143], v[142:143], v[130:131]

;     __device__ __forceinline__ void operator()(const pg8::f32x4 (&acc)[2][2][4][2], const pg8::Unit& u, int wr, int wc, int fr, int fq) const {
;     ...
;                         if (gt) { float gv[8]; unpack8(*(const u32x4*)(gt + (size_t)row * Z2_LD + gcol + bj * 128 + cl), gv);
; #pragma unroll
;                             for (int e = 0; e < 8; ++e) o[e] *= gv[e]; }
;                         bf16_t* p = dst + (size_t)row * ldc + colb + bj * 128 + cl;
;                         if (addt) { float tv[8]; unpack8(*(const u32x4*)p, tv);
; #pragma unroll
;                             for (int e = 0; e < 8; ++e) o[e] += tv[e]; }
.LBB0_363:
	v_cndmask_b32_e64 v0, 0, 1, s[52:53]
	v_cmp_ne_u32_e64 s[50:51], 1, v0
	s_andn2_b64 vcc, exec, s[52:53]
	s_cbranch_vccnz .LBB0_365
	s_waitcnt vmcnt(2)
	v_mov_b32_e32 v130, v238
	v_mov_b32_e32 v131, v239
	v_mov_b32_e32 v132, v240
	v_mov_b32_e32 v133, v241
	global_load_dwordx4 v[238:241], v[246:247], off offset:256
	v_lshlrev_b32_e32 v194, 16, v130
	v_and_b32_e32 v195, 0xffff0000, v130
	v_lshlrev_b32_e32 v130, 16, v131
	v_and_b32_e32 v131, 0xffff0000, v131
	v_pk_mul_f32 v[190:191], v[190:191], v[130:131]
	v_lshlrev_b32_e32 v130, 16, v132
	v_and_b32_e32 v131, 0xffff0000, v132
	v_pk_mul_f32 v[188:189], v[188:189], v[130:131]
	v_lshlrev_b32_e32 v130, 16, v133
	v_and_b32_e32 v131, 0xffff0000, v133
	v_pk_mul_f32 v[186:187], v[186:187], v[194:195]
	v_pk_mul_f32 v[192:193], v[192:193], v[130:131]
.LBB0_365:
	s_and_b64 vcc, exec, s[46:47]
	s_cbranch_vccnz .LBB0_367
	s_waitcnt vmcnt(4)
	v_mov_b32_e32 v130, v222
	v_mov_b32_e32 v131, v223
	v_mov_b32_e32 v132, v224
	v_mov_b32_e32 v133, v225
	global_load_dwordx4 v[222:225], v[248:249], off offset:256
	v_lshlrev_b32_e32 v194, 16, v130
	v_and_b32_e32 v195, 0xffff0000, v130
	v_lshlrev_b32_e32 v130, 16, v131
	v_and_b32_e32 v131, 0xffff0000, v131
	v_pk_add_f32 v[190:191], v[190:191], v[130:131]
	v_lshlrev_b32_e32 v130, 16, v132
	v_and_b32_e32 v131, 0xffff0000, v132
	v_pk_add_f32 v[188:189], v[188:189], v[130:131]
	v_lshlrev_b32_e32 v130, 16, v133
	v_and_b32_e32 v131, 0xffff0000, v133
	v_pk_add_f32 v[186:187], v[186:187], v[194:195]
	v_pk_add_f32 v[192:193], v[192:193], v[130:131]

;     __device__ __forceinline__ void operator()(const pg8::f32x4 (&acc)[2][2][4][2], const pg8::Unit& u, int wr, int wc, int fr, int fq) const {
;     ...
;                     const int row = rowb + ai * 128 + m * 16;
;     ...
;                         if (gt) { float gv[8]; unpack8(*(const u32x4*)(gt + (size_t)row * Z2_LD + gcol + bj * 128 + cl), gv);
; #pragma unroll
;                             for (int e = 0; e < 8; ++e) o[e] *= gv[e]; }
.LBB0_381:
	s_waitcnt lgkmcnt(0)
	v_or_b32_e32 v130, 16, v178
	v_ashrrev_i32_e32 v131, 31, v130
	v_lshlrev_b64 v[132:133], 13, v[130:131]
	s_and_b64 vcc, exec, s[50:51]
	v_lshl_add_u64 v[194:195], v[136:137], 0, v[132:133]
	s_cbranch_vccnz .LBB0_383
	s_waitcnt vmcnt(3)
	v_mov_b32_e32 v184, v234
	v_mov_b32_e32 v185, v235
	v_mov_b32_e32 v186, v236
	v_mov_b32_e32 v187, v237
	v_lshl_add_u64 v[246:247], v[250:251], 1, v[246:247]
	global_load_dwordx4 v[234:237], v[246:247], off
	v_lshlrev_b32_e32 v132, 16, v184
	v_and_b32_e32 v133, 0xffff0000, v184
	v_pk_mul_f32 v[140:141], v[140:141], v[132:133]
	v_lshlrev_b32_e32 v132, 16, v185
	v_and_b32_e32 v133, 0xffff0000, v185
	v_pk_mul_f32 v[182:183], v[182:183], v[132:133]
	v_lshlrev_b32_e32 v132, 16, v186
	v_and_b32_e32 v133, 0xffff0000, v186
	v_pk_mul_f32 v[142:143], v[142:143], v[132:133]
	v_lshlrev_b32_e32 v132, 16, v187
	v_and_b32_e32 v133, 0xffff0000, v187
	v_pk_mul_f32 v[144:145], v[144:145], v[132:133]

;     __device__ __forceinline__ void operator()(const pg8::f32x4 (&acc)[2][2][4][2], const pg8::Unit& u, int wr, int wc, int fr, int fq) const {
;     ...
;                         if (gt) { float gv[8]; unpack8(*(const u32x4*)(gt + (size_t)row * Z2_LD + gcol + bj * 128 + cl), gv);
; #pragma unroll
;                             for (int e = 0; e < 8; ++e) o[e] *= gv[e]; }
;                         bf16_t* p = dst + (size_t)row * ldc + colb + bj * 128 + cl;
;                         if (addt) { float tv[8]; unpack8(*(const u32x4*)p, tv);
; #pragma unroll
;                             for (int e = 0; e < 8; ++e) o[e] += tv[e]; }
.LBB0_390:
	s_and_b64 vcc, exec, s[50:51]
	s_cbranch_vccnz .LBB0_392
	s_waitcnt vmcnt(3)
	v_mov_b32_e32 v130, v238
	v_mov_b32_e32 v131, v239
	v_mov_b32_e32 v132, v240
	v_mov_b32_e32 v133, v241
	global_load_dwordx4 v[238:241], v[246:247], off offset:256
	v_lshlrev_b32_e32 v194, 16, v130
	v_and_b32_e32 v195, 0xffff0000, v130
	v_lshlrev_b32_e32 v130, 16, v131
	v_and_b32_e32 v131, 0xffff0000, v131
	v_pk_mul_f32 v[190:191], v[190:191], v[130:131]
	v_lshlrev_b32_e32 v130, 16, v132
	v_and_b32_e32 v131, 0xffff0000, v132
	v_pk_mul_f32 v[188:189], v[188:189], v[130:131]
	v_lshlrev_b32_e32 v130, 16, v133
	v_and_b32_e32 v131, 0xffff0000, v133
	v_pk_mul_f32 v[186:187], v[186:187], v[194:195]
	v_pk_mul_f32 v[192:193], v[192:193], v[130:131]
.LBB0_392:
	s_and_b64 vcc, exec, s[46:47]
	s_cbranch_vccnz .LBB0_394
	s_waitcnt vmcnt(5)
	v_mov_b32_e32 v130, v222
	v_mov_b32_e32 v131, v223
	v_mov_b32_e32 v132, v224
	v_mov_b32_e32 v133, v225
	global_load_dwordx4 v[222:225], v[248:249], off offset:256
	v_lshlrev_b32_e32 v194, 16, v130
	v_and_b32_e32 v195, 0xffff0000, v130
	v_lshlrev_b32_e32 v130, 16, v131
	v_and_b32_e32 v131, 0xffff0000, v131
	v_pk_add_f32 v[190:191], v[190:191], v[130:131]
	v_lshlrev_b32_e32 v130, 16, v132
	v_and_b32_e32 v131, 0xffff0000, v132
	v_pk_add_f32 v[188:189], v[188:189], v[130:131]
	v_lshlrev_b32_e32 v130, 16, v133
	v_and_b32_e32 v131, 0xffff0000, v133
	v_pk_add_f32 v[186:187], v[186:187], v[194:195]
	v_pk_add_f32 v[192:193], v[192:193], v[130:131]

;     __device__ __forceinline__ void operator()(const pg8::f32x4 (&acc)[2][2][4][2], const pg8::Unit& u, int wr, int wc, int fr, int fq) const {
;     ...
;                         bf16_t* p = dst + (size_t)row * ldc + colb + bj * 128 + cl;
;                         if (addt) { float tv[8]; unpack8(*(const u32x4*)p, tv);
; #pragma unroll
;                             for (int e = 0; e < 8; ++e) o[e] += tv[e]; }
.LBB0_400:
	s_waitcnt vmcnt(2)
	v_mov_b32_e32 v130, v242
	v_mov_b32_e32 v131, v243
	v_mov_b32_e32 v132, v244
	v_mov_b32_e32 v133, v245
	v_lshl_add_u64 v[248:249], v[250:251], 0, v[248:249]
	global_load_dwordx4 v[242:245], v[248:249], off
	v_lshlrev_b32_e32 v186, 16, v130
	v_and_b32_e32 v187, 0xffff0000, v130
	v_lshlrev_b32_e32 v130, 16, v131
	v_and_b32_e32 v131, 0xffff0000, v131
	v_pk_add_f32 v[182:183], v[182:183], v[130:131]
	v_lshlrev_b32_e32 v130, 16, v132
	v_and_b32_e32 v131, 0xffff0000, v132
	v_pk_add_f32 v[144:145], v[144:145], v[130:131]
	v_lshlrev_b32_e32 v130, 16, v133
	v_and_b32_e32 v131, 0xffff0000, v133
	v_pk_add_f32 v[140:141], v[140:141], v[186:187]
	v_pk_add_f32 v[142:143], v[142:143], v[130:131]
	s_mov_b64 s[18:19], -1
	s_and_b64 vcc, exec, s[84:85]
	s_cbranch_vccz .LBB0_358

;     __device__ __forceinline__ void operator()(const pg8::f32x4 (&acc)[2][2][4][2], const pg8::Unit& u, int wr, int wc, int fr, int fq) const {
;     ...
;                         bf16_t* p = dst + (size_t)row * ldc + colb + bj * 128 + cl;
;                         if (addt) { float tv[8]; unpack8(*(const u32x4*)p, tv);
; #pragma unroll
;                             for (int e = 0; e < 8; ++e) o[e] += tv[e]; }
.LBB0_402:
	s_waitcnt vmcnt(5)
	v_mov_b32_e32 v130, v242
	v_mov_b32_e32 v131, v243
	v_mov_b32_e32 v132, v244
	v_mov_b32_e32 v133, v245
	v_lshl_add_u64 v[248:249], v[250:251], 0, v[248:249]
	global_load_dwordx4 v[242:245], v[248:249], off
	v_lshlrev_b32_e32 v186, 16, v130
	v_and_b32_e32 v187, 0xffff0000, v130
	v_lshlrev_b32_e32 v130, 16, v131
	v_and_b32_e32 v131, 0xffff0000, v131
	v_pk_add_f32 v[182:183], v[182:183], v[130:131]
	v_lshlrev_b32_e32 v130, 16, v132
	v_and_b32_e32 v131, 0xffff0000, v132
	v_pk_add_f32 v[142:143], v[142:143], v[130:131]
	v_lshlrev_b32_e32 v130, 16, v133
	v_and_b32_e32 v131, 0xffff0000, v133
	v_pk_add_f32 v[140:141], v[140:141], v[186:187]
	v_pk_add_f32 v[144:145], v[144:145], v[130:131]
	s_and_b64 vcc, exec, s[52:53]
	s_mov_b64 s[18:19], -1
	s_cbranch_vccnz .LBB0_385

;     __device__ __forceinline__ void operator()(const pg8::f32x4 (&acc)[2][2][4][2], const pg8::Unit& u, int wr, int wc, int fr, int fq) const {
;     ...
;                         if (gt) { float gv[8]; unpack8(*(const u32x4*)(gt + (size_t)row * Z2_LD + gcol + bj * 128 + cl), gv);
; #pragma unroll
;                             for (int e = 0; e < 8; ++e) o[e] *= gv[e]; }
.LBB0_412:
	s_waitcnt lgkmcnt(0)
	v_or_b32_e32 v130, 32, v178
	v_ashrrev_i32_e32 v131, 31, v130
	v_lshlrev_b64 v[132:133], 13, v[130:131]
	s_and_b64 vcc, exec, s[50:51]
	v_lshl_add_u64 v[194:195], v[136:137], 0, v[132:133]
	s_cbranch_vccnz .LBB0_414
	s_waitcnt vmcnt(3)
	v_mov_b32_e32 v184, v234
	v_mov_b32_e32 v185, v235
	v_mov_b32_e32 v186, v236
	v_mov_b32_e32 v187, v237
	v_lshl_add_u64 v[246:247], v[250:251], 1, v[246:247]
	global_load_dwordx4 v[234:237], v[246:247], off
	v_lshlrev_b32_e32 v132, 16, v184
	v_and_b32_e32 v133, 0xffff0000, v184
	v_pk_mul_f32 v[140:141], v[140:141], v[132:133]
	v_lshlrev_b32_e32 v132, 16, v185
	v_and_b32_e32 v133, 0xffff0000, v185
	v_pk_mul_f32 v[182:183], v[182:183], v[132:133]
	v_lshlrev_b32_e32 v132, 16, v186
	v_and_b32_e32 v133, 0xffff0000, v186
	v_pk_mul_f32 v[142:143], v[142:143], v[132:133]
	v_lshlrev_b32_e32 v132, 16, v187
	v_and_b32_e32 v133, 0xffff0000, v187
	v_pk_mul_f32 v[144:145], v[144:145], v[132:133]

;     __device__ __forceinline__ void operator()(const pg8::f32x4 (&acc)[2][2][4][2], const pg8::Unit& u, int wr, int wc, int fr, int fq) const {
;     ...
;                         if (gt) { float gv[8]; unpack8(*(const u32x4*)(gt + (size_t)row * Z2_LD + gcol + bj * 128 + cl), gv);
; #pragma unroll
;                             for (int e = 0; e < 8; ++e) o[e] *= gv[e]; }
.LBB0_441:
	s_waitcnt lgkmcnt(0)
	v_or_b32_e32 v130, 48, v178
	v_ashrrev_i32_e32 v131, 31, v130
	v_lshlrev_b64 v[132:133], 13, v[130:131]
	s_and_b64 vcc, exec, s[50:51]
	v_lshl_add_u64 v[194:195], v[136:137], 0, v[132:133]
	s_cbranch_vccnz .LBB0_443
	s_waitcnt vmcnt(3)
	v_mov_b32_e32 v184, v234
	v_mov_b32_e32 v185, v235
	v_mov_b32_e32 v186, v236
	v_mov_b32_e32 v187, v237
	v_lshl_add_u64 v[246:247], v[250:251], 3, v[246:247]
	v_lshl_add_u64 v[246:247], v[250:251], 1, v[246:247]
	global_load_dwordx4 v[234:237], v[246:247], off
	v_lshlrev_b32_e32 v132, 16, v184
	v_and_b32_e32 v133, 0xffff0000, v184
	v_pk_mul_f32 v[140:141], v[140:141], v[132:133]
	v_lshlrev_b32_e32 v132, 16, v185
	v_and_b32_e32 v133, 0xffff0000, v185
	v_pk_mul_f32 v[182:183], v[182:183], v[132:133]
	v_lshlrev_b32_e32 v132, 16, v186
	v_and_b32_e32 v133, 0xffff0000, v186
	v_pk_mul_f32 v[142:143], v[142:143], v[132:133]
	v_lshlrev_b32_e32 v132, 16, v187
	v_and_b32_e32 v133, 0xffff0000, v187
	v_pk_mul_f32 v[144:145], v[144:145], v[132:133]

;     __device__ __forceinline__ void operator()(const pg8::f32x4 (&acc)[2][2][4][2], const pg8::Unit& u, int wr, int wc, int fr, int fq) const {
;     ...
;                         bf16_t* p = dst + (size_t)row * ldc + colb + bj * 128 + cl;
;                         if (addt) { float tv[8]; unpack8(*(const u32x4*)p, tv);
; #pragma unroll
;                             for (int e = 0; e < 8; ++e) o[e] += tv[e]; }
.LBB0_460:
	s_waitcnt vmcnt(5)
	v_mov_b32_e32 v130, v242
	v_mov_b32_e32 v131, v243
	v_mov_b32_e32 v132, v244
	v_mov_b32_e32 v133, v245
	v_lshl_add_u64 v[248:249], v[250:251], 2, v[248:249]
	v_lshl_add_u64 v[248:249], v[250:251], 0, v[248:249]
	global_load_dwordx4 v[242:245], v[248:249], off
	v_lshlrev_b32_e32 v186, 16, v130
	v_and_b32_e32 v187, 0xffff0000, v130
	v_lshlrev_b32_e32 v130, 16, v131
	v_and_b32_e32 v131, 0xffff0000, v131
	v_pk_add_f32 v[182:183], v[182:183], v[130:131]
	v_lshlrev_b32_e32 v130, 16, v132
	v_and_b32_e32 v131, 0xffff0000, v132
	v_pk_add_f32 v[142:143], v[142:143], v[130:131]
	v_lshlrev_b32_e32 v130, 16, v133
	v_and_b32_e32 v131, 0xffff0000, v133
	v_pk_add_f32 v[140:141], v[140:141], v[186:187]
	v_pk_add_f32 v[144:145], v[144:145], v[130:131]
	s_and_b64 vcc, exec, s[52:53]
	s_mov_b64 s[18:19], -1
	s_cbranch_vccnz .LBB0_445

;     __device__ __forceinline__ void operator()(const pg8::f32x4 (&acc)[2][2][4][2], const pg8::Unit& u, int wr, int wc, int fr, int fq) const {
;     ...
;                         if (gt) { float gv[8]; unpack8(*(const u32x4*)(gt + (size_t)row * Z2_LD + gcol + bj * 128 + cl), gv);
; #pragma unroll
;                             for (int e = 0; e < 8; ++e) o[e] *= gv[e]; }
.LBB0_470:
	v_ashrrev_i32_e32 v181, 31, v180
	s_waitcnt lgkmcnt(0)
	v_lshlrev_b64 v[130:131], 13, v[180:181]
	s_and_b64 vcc, exec, s[50:51]
	v_lshl_add_u64 v[194:195], v[136:137], 0, v[130:131]
	s_cbranch_vccnz .LBB0_472
	s_waitcnt vmcnt(3)
	v_mov_b32_e32 v130, v234
	v_mov_b32_e32 v131, v235
	v_mov_b32_e32 v132, v236
	v_mov_b32_e32 v133, v237
	v_lshl_add_u64 v[246:247], v[250:251], 1, v[246:247]
	global_load_dwordx4 v[234:237], v[246:247], off
	v_lshlrev_b32_e32 v184, 16, v130
	v_and_b32_e32 v185, 0xffff0000, v130
	v_lshlrev_b32_e32 v130, 16, v131
	v_and_b32_e32 v131, 0xffff0000, v131
	v_pk_mul_f32 v[182:183], v[182:183], v[130:131]
	v_lshlrev_b32_e32 v130, 16, v132
	v_and_b32_e32 v131, 0xffff0000, v132
	v_pk_mul_f32 v[142:143], v[142:143], v[130:131]
	v_lshlrev_b32_e32 v130, 16, v133
	v_and_b32_e32 v131, 0xffff0000, v133
	v_pk_mul_f32 v[140:141], v[140:141], v[184:185]
	v_pk_mul_f32 v[144:145], v[144:145], v[130:131]

;     __device__ __forceinline__ void operator()(const pg8::f32x4 (&acc)[2][2][4][2], const pg8::Unit& u, int wr, int wc, int fr, int fq) const {
;     ...
;                         if (gt) { float gv[8]; unpack8(*(const u32x4*)(gt + (size_t)row * Z2_LD + gcol + bj * 128 + cl), gv);
; #pragma unroll
;                             for (int e = 0; e < 8; ++e) o[e] *= gv[e]; }
.LBB0_499:
	s_waitcnt lgkmcnt(0)
	v_add_u32_e32 v130, 0x90, v178
	v_ashrrev_i32_e32 v131, 31, v130
	v_lshlrev_b64 v[132:133], 13, v[130:131]
	s_and_b64 vcc, exec, s[50:51]
	v_lshl_add_u64 v[194:195], v[136:137], 0, v[132:133]
	s_cbranch_vccnz .LBB0_501
	s_waitcnt vmcnt(3)
	v_mov_b32_e32 v184, v234
	v_mov_b32_e32 v185, v235
	v_mov_b32_e32 v186, v236
	v_mov_b32_e32 v187, v237
	v_lshl_add_u64 v[246:247], v[250:251], 1, v[246:247]
	global_load_dwordx4 v[234:237], v[246:247], off
	v_lshlrev_b32_e32 v132, 16, v184
	v_and_b32_e32 v133, 0xffff0000, v184
	v_pk_mul_f32 v[140:141], v[140:141], v[132:133]
	v_lshlrev_b32_e32 v132, 16, v185
	v_and_b32_e32 v133, 0xffff0000, v185
	v_pk_mul_f32 v[182:183], v[182:183], v[132:133]
	v_lshlrev_b32_e32 v132, 16, v186
	v_and_b32_e32 v133, 0xffff0000, v186
	v_pk_mul_f32 v[142:143], v[142:143], v[132:133]
	v_lshlrev_b32_e32 v132, 16, v187
	v_and_b32_e32 v133, 0xffff0000, v187
	v_pk_mul_f32 v[144:145], v[144:145], v[132:133]

;     __device__ __forceinline__ void operator()(const pg8::f32x4 (&acc)[2][2][4][2], const pg8::Unit& u, int wr, int wc, int fr, int fq) const {
;     ...
;                         if (gt) { float gv[8]; unpack8(*(const u32x4*)(gt + (size_t)row * Z2_LD + gcol + bj * 128 + cl), gv);
; #pragma unroll
;                             for (int e = 0; e < 8; ++e) o[e] *= gv[e]; }
.LBB0_528:
	s_waitcnt lgkmcnt(0)
	v_add_u32_e32 v130, 0xa0, v178
	v_ashrrev_i32_e32 v131, 31, v130
	v_lshlrev_b64 v[132:133], 13, v[130:131]
	s_and_b64 vcc, exec, s[50:51]
	v_lshl_add_u64 v[194:195], v[136:137], 0, v[132:133]
	s_cbranch_vccnz .LBB0_530
	s_waitcnt vmcnt(3)
	v_mov_b32_e32 v184, v234
	v_mov_b32_e32 v185, v235
	v_mov_b32_e32 v186, v236
	v_mov_b32_e32 v187, v237
	v_lshl_add_u64 v[246:247], v[250:251], 1, v[246:247]
	global_load_dwordx4 v[234:237], v[246:247], off
	v_lshlrev_b32_e32 v132, 16, v184
	v_and_b32_e32 v133, 0xffff0000, v184
	v_pk_mul_f32 v[140:141], v[140:141], v[132:133]
	v_lshlrev_b32_e32 v132, 16, v185
	v_and_b32_e32 v133, 0xffff0000, v185
	v_pk_mul_f32 v[182:183], v[182:183], v[132:133]
	v_lshlrev_b32_e32 v132, 16, v186
	v_and_b32_e32 v133, 0xffff0000, v186
	v_pk_mul_f32 v[142:143], v[142:143], v[132:133]
	v_lshlrev_b32_e32 v132, 16, v187
	v_and_b32_e32 v133, 0xffff0000, v187
	v_pk_mul_f32 v[144:145], v[144:145], v[132:133]

;     __device__ __forceinline__ void operator()(const pg8::f32x4 (&acc)[2][2][4][2], const pg8::Unit& u, int wr, int wc, int fr, int fq) const {
;     ...
;                         if (gt) { float gv[8]; unpack8(*(const u32x4*)(gt + (size_t)row * Z2_LD + gcol + bj * 128 + cl), gv);
; #pragma unroll
;                             for (int e = 0; e < 8; ++e) o[e] *= gv[e]; }
.LBB0_557:
	s_waitcnt lgkmcnt(0)
	v_add_u32_e32 v130, 0xb0, v178
	v_ashrrev_i32_e32 v131, 31, v130
	v_lshlrev_b64 v[132:133], 13, v[130:131]
	s_and_b64 vcc, exec, s[50:51]
	v_lshl_add_u64 v[190:191], v[136:137], 0, v[132:133]
	s_cbranch_vccnz .LBB0_559
	s_waitcnt vmcnt(3)
	v_mov_b32_e32 v184, v234
	v_mov_b32_e32 v185, v235
	v_mov_b32_e32 v186, v236
	v_mov_b32_e32 v187, v237
	v_lshlrev_b32_e32 v132, 16, v184
	v_and_b32_e32 v133, 0xffff0000, v184
	v_pk_mul_f32 v[140:141], v[140:141], v[132:133]
	v_lshlrev_b32_e32 v132, 16, v185
	v_and_b32_e32 v133, 0xffff0000, v185
	v_pk_mul_f32 v[182:183], v[182:183], v[132:133]
	v_lshlrev_b32_e32 v132, 16, v186
	v_and_b32_e32 v133, 0xffff0000, v186
	v_pk_mul_f32 v[142:143], v[142:143], v[132:133]
	v_lshlrev_b32_e32 v132, 16, v187
	v_and_b32_e32 v133, 0xffff0000, v187
	v_pk_mul_f32 v[144:145], v[144:145], v[132:133]

;     __device__ __forceinline__ void operator()(const pg8::f32x4 (&acc)[2][2][4][2], const pg8::Unit& u, int wr, int wc, int fr, int fq) const {
;     ...
;                         if (gt) { float gv[8]; unpack8(*(const u32x4*)(gt + (size_t)row * Z2_LD + gcol + bj * 128 + cl), gv);
; #pragma unroll
;                             for (int e = 0; e < 8; ++e) o[e] *= gv[e]; }
;                         bf16_t* p = dst + (size_t)row * ldc + colb + bj * 128 + cl;
;                         if (addt) { float tv[8]; unpack8(*(const u32x4*)p, tv);
; #pragma unroll
;                             for (int e = 0; e < 8; ++e) o[e] += tv[e]; }
.LBB0_566:
	s_and_b64 vcc, exec, s[50:51]
	s_cbranch_vccnz .LBB0_568
	s_waitcnt vmcnt(2)
	v_mov_b32_e32 v130, v238
	v_mov_b32_e32 v131, v239
	v_mov_b32_e32 v132, v240
	v_mov_b32_e32 v133, v241
	v_lshlrev_b32_e32 v134, 16, v130
	v_and_b32_e32 v135, 0xffff0000, v130
	v_lshlrev_b32_e32 v130, 16, v131
	v_and_b32_e32 v131, 0xffff0000, v131
	v_pk_mul_f32 v[186:187], v[186:187], v[130:131]
	v_lshlrev_b32_e32 v130, 16, v132
	v_and_b32_e32 v131, 0xffff0000, v132
	v_pk_mul_f32 v[184:185], v[184:185], v[130:131]
	v_lshlrev_b32_e32 v130, 16, v133
	v_and_b32_e32 v131, 0xffff0000, v133
	v_pk_mul_f32 v[138:139], v[138:139], v[134:135]
	v_pk_mul_f32 v[188:189], v[188:189], v[130:131]
.LBB0_568:
	s_and_b64 vcc, exec, s[46:47]
	s_cbranch_vccnz .LBB0_570
	s_waitcnt vmcnt(2)
	v_mov_b32_e32 v130, v222
	v_mov_b32_e32 v131, v223
	v_mov_b32_e32 v132, v224
	v_mov_b32_e32 v133, v225
	v_lshlrev_b32_e32 v134, 16, v130
	v_and_b32_e32 v135, 0xffff0000, v130
	v_lshlrev_b32_e32 v130, 16, v131
	v_and_b32_e32 v131, 0xffff0000, v131
	v_pk_add_f32 v[186:187], v[186:187], v[130:131]
	v_lshlrev_b32_e32 v130, 16, v132
	v_and_b32_e32 v131, 0xffff0000, v132
	v_pk_add_f32 v[184:185], v[184:185], v[130:131]
	v_lshlrev_b32_e32 v130, 16, v133
	v_and_b32_e32 v131, 0xffff0000, v133
	v_pk_add_f32 v[138:139], v[138:139], v[134:135]
	v_pk_add_f32 v[188:189], v[188:189], v[130:131]

;     __device__ __forceinline__ void operator()(const pg8::f32x4 (&acc)[2][2][4][2], const pg8::Unit& u, int wr, int wc, int fr, int fq) const {
;     ...
;                         bf16_t* p = dst + (size_t)row * ldc + colb + bj * 128 + cl;
;                         if (addt) { float tv[8]; unpack8(*(const u32x4*)p, tv);
; #pragma unroll
;                             for (int e = 0; e < 8; ++e) o[e] += tv[e]; }
.LBB0_576:
	s_waitcnt vmcnt(4)
	v_mov_b32_e32 v130, v242
	v_mov_b32_e32 v131, v243
	v_mov_b32_e32 v132, v244
	v_mov_b32_e32 v133, v245
	v_lshlrev_b32_e32 v138, 16, v130
	v_and_b32_e32 v139, 0xffff0000, v130
	v_lshlrev_b32_e32 v130, 16, v131
	v_and_b32_e32 v131, 0xffff0000, v131
	v_pk_add_f32 v[182:183], v[182:183], v[130:131]
	v_lshlrev_b32_e32 v130, 16, v132
	v_and_b32_e32 v131, 0xffff0000, v132
	v_pk_add_f32 v[142:143], v[142:143], v[130:131]
	v_lshlrev_b32_e32 v130, 16, v133
	v_and_b32_e32 v131, 0xffff0000, v133
	v_pk_add_f32 v[140:141], v[140:141], v[138:139]
	v_pk_add_f32 v[144:145], v[144:145], v[130:131]
	s_and_b64 vcc, exec, s[52:53]
	s_mov_b64 s[18:19], -1
	s_cbranch_vccnz .LBB0_561

; #define PG8_BAR __builtin_amdgcn_s_barrier()
; template <class Epi, class Sched, bool ALIGN_EPI = false, bool SP2 = false>
; __device__ __forceinline__ void gemm_phase(PG8_LAS unsigned char* lds, int tid_in, const Gemm g, const Sched& S, const Epi& E) {
;     ...
;         cur = nxt; cA = nA; cB = nB; ++ui;
;         if constexpr (ALIGN_EPI) { if (wr == 1) PG8_BAR; }
;     }
.LBB0_620:
	s_andn2_b64 vcc, exec, s[56:57]
	s_cbranch_vccnz .LBB0_269
	s_barrier
	s_branch .LBB0_269
	s_nop 0
	s_nop 0
	s_nop 0
	s_nop 0
	s_nop 0
	s_nop 0
	s_nop 0
	s_nop 0
	s_nop 0
	s_nop 0
	s_nop 0
	s_nop 0
	s_nop 0
	s_nop 0
	s_nop 0
	s_nop 0
	s_nop 0
	s_nop 0
	s_nop 0
	s_nop 0
	s_nop 0
	s_nop 0
	s_nop 0
	s_nop 0
	s_nop 0
	s_nop 0
	s_nop 0
	s_nop 0
	s_nop 0
	s_nop 0
	s_nop 0
	s_nop 0
	s_nop 0
	s_nop 0
	s_nop 0
	s_nop 0
	s_nop 0
	s_nop 0
	s_nop 0
	s_nop 0
	s_nop 0
	s_nop 0
	s_nop 0
	s_nop 0
	s_nop 0
	s_nop 0
	s_nop 0
	s_nop 0
	s_nop 0
	s_nop 0
	s_nop 0
	s_nop 0
	s_nop 0
	s_nop 0
	s_nop 0
	s_nop 0
	s_nop 0
	s_nop 0
	s_nop 0
	s_nop 0
	s_nop 0
	s_nop 0
	s_nop 0
	s_nop 0
	s_nop 0
	s_nop 0
	s_nop 0
	s_nop 0
	s_nop 0
	s_nop 0
	s_nop 0
	s_nop 0
	s_nop 0
	s_nop 0
	s_nop 0
	s_nop 0
	s_nop 0
	s_nop 0
	s_nop 0
	s_nop 0
	s_nop 0
	s_nop 0
	s_nop 0
	s_nop 0
	s_nop 0
	s_nop 0
	s_nop 0
	s_nop 0
	s_nop 0
	s_nop 0
	s_nop 0
	s_nop 0
	s_nop 0
	s_nop 0
	s_nop 0
	s_nop 0
	s_nop 0
	s_nop 0
	s_nop 0
	s_nop 0
	s_nop 0
	s_nop 0
	s_nop 0
	s_nop 0
	s_nop 0
	s_nop 0
	s_nop 0
	s_nop 0
	s_nop 0
	s_nop 0
	s_nop 0
	s_nop 0
	s_nop 0
	s_nop 0
	s_nop 0
	s_nop 0
	s_nop 0
	s_nop 0
	s_nop 0
	s_nop 0
	s_nop 0
	s_nop 0
	s_nop 0
	s_nop 0
	s_nop 0
	s_nop 0
	s_nop 0
	s_nop 0
	s_nop 0
	s_nop 0
	s_nop 0
	s_nop 0
	s_nop 0
	s_nop 0
	s_nop 0
	s_nop 0
	s_nop 0
	s_nop 0
	s_nop 0
	s_nop 0
	s_nop 0
	s_nop 0
	s_nop 0
	s_nop 0
	s_nop 0
	s_nop 0
	s_nop 0
	s_nop 0
	s_nop 0
	s_nop 0
	s_nop 0
	s_nop 0
	s_nop 0
	s_nop 0
	s_nop 0
	s_nop 0
	s_nop 0
	s_nop 0
	s_nop 0
	s_nop 0
	s_nop 0
	s_nop 0
	s_nop 0
	s_nop 0
	s_nop 0
	s_nop 0
	s_nop 0
	s_nop 0
	s_nop 0
	s_nop 0
	s_nop 0
	s_nop 0
	s_nop 0
	s_nop 0
	s_nop 0
	s_nop 0
	s_nop 0
	s_nop 0
	s_nop 0
	s_nop 0
	s_nop 0
	s_nop 0
	s_nop 0
	s_nop 0
	s_nop 0
	s_nop 0
	s_nop 0
	s_nop 0
	s_nop 0
	s_nop 0
	s_nop 0
	s_nop 0
	s_nop 0
	s_nop 0
	s_nop 0
	s_nop 0
	s_nop 0
	s_nop 0
	s_nop 0
	s_nop 0
	s_nop 0
	s_nop 0
	s_nop 0
	s_nop 0
	s_nop 0
	s_nop 0
	s_nop 0
	s_nop 0
	s_nop 0
	s_nop 0
	s_nop 0
	s_nop 0
	s_nop 0
	s_nop 0
	s_nop 0
	s_nop 0
	s_nop 0
	s_nop 0
	s_nop 0
	s_nop 0
	s_nop 0
	s_nop 0
	s_nop 0
	s_nop 0
	s_nop 0
	s_nop 0
	s_nop 0
	s_nop 0
	s_nop 0
	s_nop 0
	s_nop 0
	s_nop 0
	s_nop 0
	s_nop 0
	s_nop 0
	s_nop 0
	s_nop 0
	s_nop 0
	s_nop 0
	s_nop 0
	s_nop 0
	s_nop 0
	s_nop 0
	s_nop 0
	s_nop 0
	s_nop 0
	s_nop 0
	s_nop 0
	s_nop 0
	s_nop 0
	s_nop 0
	s_nop 0
	s_nop 0
	s_nop 0
	s_nop 0
	s_nop 0
	s_nop 0
	s_nop 0
	s_nop 0
	s_nop 0
	s_nop 0
	s_nop 0
	s_nop 0
	s_nop 0
	s_nop 0
	s_nop 0
	s_nop 0
	s_nop 0
	s_nop 0
	s_nop 0
	s_nop 0
	s_nop 0
	s_nop 0
	s_nop 0
	s_nop 0
	s_nop 0
	s_nop 0
	s_nop 0
	s_nop 0
	s_nop 0
	s_nop 0
	s_nop 0
	s_nop 0
	s_nop 0
	s_nop 0
	s_nop 0
	s_nop 0
	s_nop 0
	s_nop 0
	s_nop 0
	s_nop 0
	s_nop 0
	s_nop 0
	s_nop 0
	s_nop 0
	s_nop 0
	s_nop 0
	s_nop 0
	s_nop 0
	s_nop 0
	s_nop 0
	s_nop 0
	s_nop 0
	s_nop 0
	s_nop 0
	s_nop 0
	s_nop 0
	s_nop 0
	s_nop 0
	s_nop 0
	s_nop 0
	s_nop 0
	s_nop 0
	s_nop 0
	s_nop 0
	s_nop 0
	s_nop 0
	s_nop 0
	s_nop 0
	s_nop 0
	s_nop 0
	s_nop 0
	s_nop 0
	s_nop 0
	s_nop 0
	s_nop 0
	s_nop 0
	s_nop 0
	s_nop 0
	s_nop 0
	s_nop 0
	s_nop 0
	s_nop 0
	s_nop 0
	s_nop 0
	s_nop 0
	s_nop 0
	s_nop 0
	s_nop 0
	s_nop 0
	s_nop 0
	s_nop 0
	s_nop 0
	s_nop 0
	s_nop 0
	s_nop 0
	s_nop 0
	s_nop 0
	s_nop 0
	s_nop 0
	s_nop 0
	s_nop 0
	s_nop 0
	s_nop 0
	s_nop 0
	s_nop 0
	s_nop 0
	s_nop 0
	s_nop 0
	s_nop 0
	s_nop 0
	s_nop 0
	s_nop 0
	s_nop 0
	s_nop 0
	s_nop 0
	s_nop 0
	s_nop 0
	s_nop 0
	s_nop 0
	s_nop 0
	s_nop 0
	s_nop 0
	s_nop 0
	s_nop 0
	s_nop 0
	s_nop 0
	s_nop 0
	s_nop 0
	s_nop 0
	s_nop 0
	s_nop 0
	s_nop 0
	s_nop 0
	s_nop 0
	s_nop 0
	s_nop 0
	s_nop 0
	s_nop 0
	s_nop 0
	s_nop 0
	s_nop 0
	s_nop 0
	s_nop 0
	s_nop 0
	s_nop 0
	s_nop 0
	s_nop 0
	s_nop 0
	s_nop 0
	s_nop 0
	s_nop 0
	s_nop 0
	s_nop 0
	s_nop 0
	s_nop 0
	s_nop 0
	s_nop 0
	s_nop 0
	s_nop 0
	s_nop 0
	s_nop 0
	s_nop 0
	s_nop 0
	s_nop 0
	s_nop 0
	s_nop 0
	s_nop 0
	s_nop 0
	s_nop 0
	s_nop 0
	s_nop 0
	s_nop 0
	s_nop 0
	s_nop 0
	s_nop 0
	s_nop 0
	s_nop 0
	s_nop 0
	s_nop 0
	s_nop 0
	s_nop 0
	s_nop 0
	s_nop 0
	s_nop 0
	s_nop 0
	s_nop 0
	s_nop 0
	s_nop 0
	s_nop 0
	s_nop 0
	s_nop 0
	s_nop 0
	s_nop 0
	s_nop 0
	s_nop 0
	s_nop 0
	s_nop 0
	s_nop 0
	s_nop 0
	s_nop 0
	s_nop 0
	s_nop 0
	s_nop 0
	s_nop 0
	s_nop 0
	s_nop 0
	s_nop 0
	s_nop 0
	s_nop 0
	s_nop 0
	s_nop 0
	s_nop 0
	s_nop 0
	s_nop 0
	s_nop 0
	s_nop 0
	s_nop 0
	s_nop 0
	s_nop 0
	s_nop 0
	s_nop 0
	s_nop 0
	s_nop 0
	s_nop 0
	s_nop 0
	s_nop 0
	s_nop 0
	s_nop 0
	s_nop 0
	s_nop 0
	s_nop 0
	s_nop 0
	s_nop 0
	s_nop 0
	s_nop 0
	s_nop 0
	s_nop 0
	s_nop 0
	s_nop 0
	s_nop 0
	s_nop 0
	s_nop 0
	s_nop 0
	s_nop 0
	s_nop 0
	s_nop 0
	s_nop 0
	s_nop 0
	s_nop 0
	s_nop 0
	s_nop 0
	s_nop 0
	s_nop 0
	s_nop 0
	s_nop 0
	s_nop 0
	s_nop 0
	s_nop 0
	s_nop 0
	s_nop 0
	s_nop 0
	s_nop 0
	s_nop 0
	s_nop 0
	s_nop 0
	s_nop 0
	s_nop 0
	s_nop 0
	s_nop 0
	s_nop 0
	s_nop 0
	s_nop 0
	s_nop 0
	s_nop 0
	s_nop 0
	s_nop 0
	s_nop 0
	s_nop 0
	s_nop 0
	s_nop 0
	s_nop 0
	s_nop 0
	s_nop 0
	s_nop 0
	s_nop 0
	s_nop 0
	s_nop 0
	s_nop 0
	s_nop 0
	s_nop 0
	s_nop 0
	s_nop 0
	s_nop 0
	s_nop 0
	s_nop 0
	s_nop 0
	s_nop 0
	s_nop 0
	s_nop 0
	s_nop 0
	s_nop 0
	s_nop 0
	s_nop 0
	s_nop 0
	s_nop 0
	s_nop 0
	s_nop 0
	s_nop 0
	s_nop 0
	s_nop 0
	s_nop 0
	s_nop 0
	s_nop 0
	s_nop 0
	s_nop 0
	s_nop 0
	s_nop 0
	s_nop 0
	s_nop 0
	s_nop 0
	s_nop 0
	s_nop 0
	s_nop 0
	s_nop 0
	s_nop 0
	s_nop 0
	s_nop 0
	s_nop 0
	s_nop 0
	s_nop 0
	s_nop 0
	s_nop 0
	s_nop 0
	s_nop 0
	s_nop 0
	s_nop 0
	s_nop 0
	s_nop 0
	s_nop 0
	s_nop 0
	s_nop 0
	s_nop 0
	s_nop 0
	s_nop 0
	s_nop 0
	s_nop 0
	s_nop 0
	s_nop 0
	s_nop 0
	s_nop 0
	s_nop 0
	s_nop 0
	s_nop 0
	s_nop 0
	s_nop 0
	s_nop 0
	s_nop 0
	s_nop 0
	s_nop 0
	s_nop 0
	s_nop 0
	s_nop 0
	s_nop 0
	s_nop 0
; #define PG8_BAR __builtin_amdgcn_s_barrier()
; template <class Epi, class Sched, bool ALIGN_EPI = false, bool SP2 = false>
; __device__ __forceinline__ void gemm_phase(PG8_LAS unsigned char* lds, int tid_in, const Gemm g, const Sched& S, const Epi& E) {
;     ...
;         if constexpr (ALIGN_EPI) { if (wr == 1) PG8_BAR; }
;     }
	s_nop 0
	s_nop 0
	s_nop 0
	s_nop 0
	s_nop 0
	s_nop 0
	s_nop 0
	s_nop 0
	s_nop 0
	s_nop 0
	s_nop 0
	s_nop 0
	s_nop 0
	s_nop 0
	s_nop 0
	s_nop 0
	s_nop 0
	s_nop 0
	s_nop 0
	s_nop 0
	s_nop 0
	s_nop 0
	s_nop 0
	s_nop 0
	s_nop 0
	s_nop 0
	s_nop 0
	s_nop 0
	s_nop 0
	s_nop 0
	s_nop 0
	s_nop 0
	s_nop 0
	s_nop 0
	s_nop 0
	s_nop 0
	s_nop 0
	s_nop 0
	s_nop 0
	s_nop 0
	s_nop 0
	s_nop 0
	s_nop 0
	s_nop 0
	s_nop 0
	s_nop 0
	s_nop 0
	s_nop 0
	s_nop 0
	s_nop 0
	s_nop 0
	s_nop 0
	s_nop 0
	s_nop 0
	s_nop 0
	s_nop 0
	s_nop 0
	s_nop 0
	s_nop 0
	s_nop 0
	s_nop 0
	s_nop 0
	s_nop 0
	s_nop 0
	s_nop 0
	s_nop 0
	s_nop 0
	s_nop 0
	s_nop 0
	s_nop 0
	s_nop 0
	s_nop 0
	s_nop 0
	s_nop 0
	s_nop 0
	s_nop 0
	s_nop 0
	s_nop 0
	s_nop 0
	s_nop 0
	s_nop 0
	s_nop 0
	s_nop 0
	s_nop 0
	s_nop 0
	s_nop 0
	s_nop 0
	s_nop 0
	s_nop 0
	s_nop 0
	s_nop 0
	s_nop 0
	s_nop 0
	s_nop 0
	s_nop 0
	s_nop 0
	s_nop 0
	s_nop 0
	s_nop 0
	s_nop 0
	s_nop 0
	s_nop 0
	s_nop 0
	s_nop 0
	s_nop 0
	s_nop 0
	s_nop 0
	s_nop 0
	s_nop 0
	s_nop 0
	s_nop 0
	s_nop 0
	s_nop 0
	s_nop 0
	s_nop 0
	s_nop 0
	s_nop 0
	s_nop 0
	s_nop 0
	s_nop 0
	s_nop 0
	s_nop 0
	s_nop 0
	s_nop 0
	s_nop 0
	s_nop 0
	s_nop 0
	s_nop 0
	s_nop 0
	s_nop 0
	s_nop 0
	s_nop 0
	s_nop 0
	s_nop 0
	s_nop 0
	s_nop 0
	s_nop 0
	s_nop 0
	s_nop 0
	s_nop 0
	s_nop 0
	s_nop 0
	s_nop 0
	s_nop 0
	s_nop 0
	s_nop 0
	s_nop 0
	s_nop 0
	s_nop 0
	s_nop 0
	s_nop 0
	s_nop 0
	s_nop 0
	s_nop 0
	s_nop 0
	s_nop 0
	s_nop 0
	s_nop 0
	s_nop 0
	s_nop 0
	s_nop 0
	s_nop 0
	s_nop 0
	s_nop 0
	s_nop 0
	s_nop 0
	s_nop 0
	s_nop 0
	s_nop 0
	s_nop 0
	s_nop 0
	s_nop 0
	s_nop 0
	s_nop 0
	s_nop 0
	s_nop 0
	s_nop 0
	s_nop 0
	s_nop 0
	s_nop 0
	s_nop 0
	s_nop 0
	s_nop 0
	s_nop 0
	s_nop 0
	s_nop 0
	s_nop 0
	s_nop 0
	s_nop 0
	s_nop 0
	s_nop 0
	s_nop 0
	s_nop 0
	s_nop 0
	s_nop 0
	s_nop 0
	s_nop 0
	s_nop 0
	s_nop 0
	s_nop 0
	s_nop 0
	s_nop 0
	s_nop 0
	s_nop 0
	s_nop 0
	s_nop 0
	s_nop 0
	s_nop 0
	s_nop 0
	s_nop 0
	s_nop 0
	s_nop 0
	s_nop 0
	s_nop 0
	s_nop 0
	s_nop 0
	s_nop 0
	s_nop 0
	s_nop 0
	s_nop 0
	s_nop 0
	s_nop 0
	s_nop 0
	s_nop 0
	s_nop 0
	s_nop 0
	s_nop 0
	s_nop 0
	s_nop 0
	s_nop 0
	s_nop 0
	s_nop 0
	s_nop 0
	s_nop 0
	s_nop 0
	s_nop 0
	s_nop 0
	s_nop 0
	s_nop 0
	s_nop 0
	s_nop 0
	s_nop 0
	s_nop 0
	s_nop 0
	s_nop 0
	s_nop 0
	s_nop 0
	s_nop 0
	s_nop 0
	s_nop 0
	s_nop 0
	s_nop 0
	s_nop 0
	s_nop 0
	s_nop 0
	s_nop 0
	s_nop 0
	s_nop 0
	s_nop 0
	s_nop 0
	s_nop 0
	s_nop 0
	s_nop 0
	s_nop 0
	s_nop 0
	s_nop 0
	s_nop 0
	s_nop 0
	s_nop 0
	s_nop 0
	s_nop 0
	s_nop 0
	s_nop 0
	s_nop 0
	s_nop 0
	s_nop 0
	s_nop 0
	s_nop 0
	s_nop 0
	s_nop 0
	s_nop 0
	s_nop 0
	s_nop 0
	s_nop 0
	s_nop 0
	s_nop 0
	s_nop 0
	s_nop 0
	s_nop 0
	s_nop 0
	s_nop 0
	s_nop 0
	s_nop 0
	s_nop 0
	s_nop 0
	s_nop 0
	s_nop 0
	s_nop 0
	s_nop 0
	s_nop 0
	s_nop 0
	s_nop 0
	s_nop 0
	s_nop 0
	s_nop 0
	s_nop 0
	s_nop 0
	s_nop 0
	s_nop 0
	s_nop 0
	s_nop 0
	s_nop 0
	s_nop 0
	s_nop 0
	s_nop 0
	s_nop 0
	s_nop 0
	s_nop 0
	s_nop 0
	s_nop 0
	s_nop 0
	s_nop 0
	s_nop 0
	s_nop 0
	s_nop 0
	s_nop 0
	s_nop 0
	s_nop 0
	s_nop 0
	s_nop 0
	s_nop 0
	s_nop 0
	s_nop 0
	s_nop 0
	s_nop 0
	s_nop 0
	s_nop 0
	s_nop 0
	s_nop 0
	s_nop 0
	s_nop 0
	s_nop 0
	s_nop 0
	s_nop 0
	s_nop 0
	s_nop 0
	s_nop 0
	s_nop 0
	s_nop 0
	s_nop 0
	s_nop 0
	s_nop 0
	s_nop 0
	s_nop 0
	s_nop 0
	s_nop 0
	s_nop 0
	s_nop 0
	s_nop 0
	s_nop 0
	s_nop 0
	s_nop 0
	s_nop 0
	s_nop 0
	s_nop 0
	s_nop 0
	s_nop 0
	s_nop 0
	s_nop 0
	s_nop 0
	s_nop 0
	s_nop 0
	s_nop 0
	s_nop 0
	s_nop 0
	s_nop 0
	s_nop 0
	s_nop 0
	s_nop 0
	s_nop 0
	s_nop 0
	s_nop 0
	s_nop 0
	s_nop 0
	s_nop 0
	s_nop 0
	s_nop 0
	s_nop 0
	s_nop 0
	s_nop 0
	s_nop 0
	s_nop 0
	s_nop 0
	s_nop 0
	s_nop 0
	s_nop 0
	s_nop 0
	s_nop 0
	s_nop 0
	s_nop 0
	s_nop 0
	s_nop 0
	s_nop 0
	s_nop 0
	s_nop 0
	s_nop 0
	s_nop 0
	s_nop 0
	s_nop 0
	s_nop 0
	s_nop 0
	s_nop 0
	s_nop 0
	s_nop 0
	s_nop 0
	s_nop 0
	s_nop 0
	s_nop 0
	s_nop 0
	s_nop 0
	s_nop 0
	s_nop 0
	s_nop 0
	s_nop 0
	s_nop 0
	s_nop 0
	s_nop 0
	s_nop 0
	s_nop 0
	s_nop 0
	s_nop 0
	s_nop 0
	s_nop 0
	s_nop 0
	s_nop 0
	s_nop 0
	s_nop 0
	s_nop 0
	s_nop 0
	s_nop 0
	s_nop 0
	s_nop 0
	s_nop 0
	s_nop 0
	s_nop 0
	s_nop 0
	s_nop 0
	s_nop 0
	s_nop 0
	s_nop 0
	s_nop 0
	s_nop 0
	s_nop 0
	s_nop 0
	s_nop 0
	s_nop 0
	s_nop 0
	s_nop 0
	s_nop 0
	s_nop 0
	s_nop 0
	s_nop 0
	s_nop 0
	s_nop 0
	s_nop 0
	s_nop 0
	s_nop 0
	s_nop 0
	s_nop 0
	s_nop 0
	s_nop 0
	s_nop 0
	s_nop 0
	s_nop 0
	s_nop 0
	s_nop 0
	s_nop 0
	s_nop 0
	s_nop 0
	s_nop 0
	s_nop 0
	s_nop 0
	s_nop 0
	s_nop 0
	s_nop 0
	s_nop 0
	s_nop 0
	s_nop 0
	s_nop 0
	s_nop 0
	s_nop 0
	s_nop 0
	s_nop 0
	s_nop 0
	s_nop 0
	s_nop 0
	s_nop 0
	s_nop 0
	s_nop 0
	s_nop 0
	s_nop 0
	s_nop 0
	s_nop 0
	s_nop 0
	s_nop 0
	s_nop 0
	s_nop 0
	s_nop 0
	s_nop 0
	s_nop 0
	s_nop 0
	s_nop 0
	s_nop 0
	s_nop 0
	s_nop 0
	s_nop 0
	s_nop 0
	s_nop 0
	s_nop 0
	s_nop 0
	s_nop 0
	s_nop 0
	s_nop 0
	s_nop 0
	s_nop 0
	s_nop 0
	s_nop 0
	s_nop 0
	s_nop 0
	s_nop 0
	s_nop 0
	s_nop 0
	s_nop 0
	s_nop 0
	s_nop 0
	s_nop 0
	s_nop 0
	s_nop 0
	s_nop 0
	s_nop 0
	s_nop 0
	s_nop 0
	s_nop 0
	s_nop 0
	s_nop 0
	s_nop 0
	s_nop 0
	s_nop 0
	s_nop 0
	s_nop 0
	s_nop 0
	s_nop 0
	s_nop 0
	s_nop 0
	s_nop 0
	s_nop 0
	s_nop 0
	s_nop 0
	s_nop 0
	s_nop 0
	s_nop 0
	s_nop 0
	s_nop 0
	s_nop 0
	s_nop 0
	s_nop 0
	s_nop 0
	s_nop 0
	s_nop 0
	s_nop 0
	s_nop 0
	s_nop 0
	s_nop 0
	s_nop 0
	s_nop 0
	s_nop 0
	s_nop 0
	s_nop 0
	s_nop 0
	s_nop 0
	s_nop 0
	s_nop 0
	s_nop 0
	s_nop 0
	s_nop 0
	s_nop 0
	s_nop 0
	s_nop 0
	s_nop 0
	s_nop 0
	s_nop 0
	s_nop 0
	s_nop 0
	s_nop 0
	s_nop 0
	s_nop 0
	s_nop 0
	s_nop 0
	s_nop 0
	s_nop 0
	s_nop 0
	s_nop 0
	s_nop 0
	s_nop 0
	s_nop 0
	s_nop 0
	s_nop 0
	s_nop 0
	s_nop 0
	s_nop 0
	s_nop 0
	s_nop 0
	s_nop 0
	s_nop 0
	s_nop 0
	s_nop 0
	s_nop 0
	s_nop 0
	s_nop 0
	s_nop 0
	s_nop 0
	s_nop 0
	s_nop 0
	s_nop 0
	s_nop 0
	s_nop 0
; #define PG8_BAR __builtin_amdgcn_s_barrier()
; template <class Epi, class Sched, bool ALIGN_EPI = false, bool SP2 = false>
; __device__ __forceinline__ void gemm_phase(PG8_LAS unsigned char* lds, int tid_in, const Gemm g, const Sched& S, const Epi& E) {
;     ...
;         if constexpr (ALIGN_EPI) { if (wr == 1) PG8_BAR; }
;     }
	s_nop 0
	s_nop 0
	s_nop 0
	s_nop 0
	s_nop 0
	s_nop 0
	s_nop 0
	s_nop 0
	s_nop 0
	s_nop 0
	s_nop 0
	s_nop 0
	s_nop 0
	s_nop 0
	s_nop 0
	s_nop 0
	s_nop 0
	s_nop 0
	s_nop 0
	s_nop 0
	s_nop 0
	s_nop 0
	s_nop 0
	s_nop 0
	s_nop 0
	s_nop 0
	s_nop 0
	s_nop 0
	s_nop 0
	s_nop 0
	s_nop 0
	s_nop 0
	s_nop 0
	s_nop 0
	s_nop 0
	s_nop 0
	s_nop 0
	s_nop 0
	s_nop 0
	s_nop 0
	s_nop 0
	s_nop 0
	s_nop 0
	s_nop 0
	s_nop 0
	s_nop 0
	s_nop 0
	s_nop 0
	s_nop 0
	s_nop 0
	s_nop 0
	s_nop 0
	s_nop 0
	s_nop 0
	s_nop 0
	s_nop 0
	s_nop 0
	s_nop 0
	s_nop 0
	s_nop 0
	s_nop 0
	s_nop 0
	s_nop 0
	s_nop 0
	s_nop 0
	s_nop 0
	s_nop 0
	s_nop 0
	s_nop 0
	s_nop 0
	s_nop 0
	s_nop 0
	s_nop 0
	s_nop 0
	s_nop 0
	s_nop 0
	s_nop 0
	s_nop 0
	s_nop 0
	s_nop 0
	s_nop 0
	s_nop 0
	s_nop 0
	s_nop 0
	s_nop 0
	s_nop 0
	s_nop 0
	s_nop 0
	s_nop 0
	s_nop 0
	s_nop 0
	s_nop 0
	s_nop 0
	s_nop 0
	s_nop 0
	s_nop 0
	s_nop 0
	s_nop 0
	s_nop 0
	s_nop 0
	s_nop 0
	s_nop 0
	s_nop 0
	s_nop 0
	s_nop 0
	s_nop 0
	s_nop 0
	s_nop 0
	s_nop 0
	s_nop 0
	s_nop 0
	s_nop 0
	s_nop 0
	s_nop 0
	s_nop 0
	s_nop 0
	s_nop 0
	s_nop 0
	s_nop 0
	s_nop 0
	s_nop 0
	s_nop 0
	s_nop 0
	s_nop 0
	s_nop 0
	s_nop 0
	s_nop 0
	s_nop 0
	s_nop 0
	s_nop 0
	s_nop 0
	s_nop 0
	s_nop 0
	s_nop 0
	s_nop 0
	s_nop 0
	s_nop 0
	s_nop 0
	s_nop 0
	s_nop 0
	s_nop 0
	s_nop 0
	s_nop 0
	s_nop 0
	s_nop 0
	s_nop 0
	s_nop 0
	s_nop 0
	s_nop 0
	s_nop 0
	s_nop 0
	s_nop 0
	s_nop 0
	s_nop 0
	s_nop 0
	s_nop 0
	s_nop 0
	s_nop 0
	s_nop 0
	s_nop 0
	s_nop 0
	s_nop 0
	s_nop 0
	s_nop 0
	s_nop 0
	s_nop 0
	s_nop 0
	s_nop 0
	s_nop 0
	s_nop 0
	s_nop 0
	s_nop 0
	s_nop 0
	s_nop 0
	s_nop 0
	s_nop 0
	s_nop 0
	s_nop 0
	s_nop 0
	s_nop 0
	s_nop 0
	s_nop 0
	s_nop 0
	s_nop 0
	s_nop 0
	s_nop 0
	s_nop 0
	s_nop 0
	s_nop 0
	s_nop 0
	s_nop 0
	s_nop 0
	s_nop 0
	s_nop 0
	s_nop 0
	s_nop 0
	s_nop 0
	s_nop 0
	s_nop 0
	s_nop 0
	s_nop 0
	s_nop 0
	s_nop 0
	s_nop 0
	s_nop 0
	s_nop 0
	s_nop 0
	s_nop 0
	s_nop 0
	s_nop 0
	s_nop 0
	s_nop 0
	s_nop 0
	s_nop 0
	s_nop 0
	s_nop 0
	s_nop 0
	s_nop 0
	s_nop 0
	s_nop 0
	s_nop 0
	s_nop 0
	s_nop 0
	s_nop 0
	s_nop 0
	s_nop 0
	s_nop 0
	s_nop 0
	s_nop 0
	s_nop 0
	s_nop 0
	s_nop 0
	s_nop 0
	s_nop 0
	s_nop 0
	s_nop 0
	s_nop 0
	s_nop 0
	s_nop 0
	s_nop 0
	s_nop 0
	s_nop 0
	s_nop 0
	s_nop 0
	s_nop 0
	s_nop 0
	s_nop 0
	s_nop 0
	s_nop 0
	s_nop 0
	s_nop 0
	s_nop 0
	s_nop 0
	s_nop 0
	s_nop 0
	s_nop 0
	s_nop 0
	s_nop 0
	s_nop 0
	s_nop 0
	s_nop 0
	s_nop 0
	s_nop 0
	s_nop 0
	s_nop 0
	s_nop 0
	s_nop 0
	s_nop 0
	s_nop 0
	s_nop 0
	s_nop 0
	s_nop 0
	s_nop 0
	s_nop 0
	s_nop 0
	s_nop 0
	s_nop 0
	s_nop 0
	s_nop 0
	s_nop 0
	s_nop 0
	s_nop 0
	s_nop 0
	s_nop 0
	s_nop 0
	s_nop 0
	s_nop 0
	s_nop 0
	s_nop 0
	s_nop 0
	s_nop 0
	s_nop 0
	s_nop 0
	s_nop 0
	s_nop 0
	s_nop 0
	s_nop 0
	s_nop 0
	s_nop 0
	s_nop 0
	s_nop 0
	s_nop 0
	s_nop 0
	s_nop 0
	s_nop 0
	s_nop 0
	s_nop 0
	s_nop 0
	s_nop 0
	s_nop 0
	s_nop 0
	s_nop 0
	s_nop 0
	s_nop 0
	s_nop 0
	s_nop 0
	s_nop 0
	s_nop 0
	s_nop 0
	s_nop 0
	s_nop 0
	s_nop 0
	s_nop 0
	s_nop 0
	s_nop 0
	s_nop 0
	s_nop 0
	s_nop 0
	s_nop 0
	s_nop 0
	s_nop 0
	s_nop 0
	s_nop 0
	s_nop 0
	s_nop 0
	s_nop 0
	s_nop 0
	s_nop 0
	s_nop 0
	s_nop 0
	s_nop 0
	s_nop 0
	s_nop 0
	s_nop 0
	s_nop 0
	s_nop 0
	s_nop 0
	s_nop 0
	s_nop 0
	s_nop 0
	s_nop 0
	s_nop 0
	s_nop 0
	s_nop 0
	s_nop 0
	s_nop 0
	s_nop 0
	s_nop 0
	s_nop 0
	s_nop 0
	s_nop 0
	s_nop 0
	s_nop 0
	s_nop 0
	s_nop 0
	s_nop 0
	s_nop 0
	s_nop 0
	s_nop 0
	s_nop 0
	s_nop 0
	s_nop 0
	s_nop 0
	s_nop 0
	s_nop 0
	s_nop 0
	s_nop 0
	s_nop 0
	s_nop 0
	s_nop 0
	s_nop 0
	s_nop 0
	s_nop 0
	s_nop 0
	s_nop 0
	s_nop 0
	s_nop 0
	s_nop 0
	s_nop 0
	s_nop 0
	s_nop 0
	s_nop 0
	s_nop 0
	s_nop 0
	s_nop 0
	s_nop 0
	s_nop 0
	s_nop 0
	s_nop 0
	s_nop 0
	s_nop 0
	s_nop 0
	s_nop 0
	s_nop 0
	s_nop 0
	s_nop 0
	s_nop 0
	s_nop 0
	s_nop 0
	s_nop 0
	s_nop 0
	s_nop 0
	s_nop 0
	s_nop 0
	s_nop 0
	s_nop 0
	s_nop 0
	s_nop 0
	s_nop 0
	s_nop 0
	s_nop 0
	s_nop 0
	s_nop 0
	s_nop 0
	s_nop 0
	s_nop 0
	s_nop 0
	s_nop 0
	s_nop 0
	s_nop 0
	s_nop 0
	s_nop 0
	s_nop 0
	s_nop 0
	s_nop 0
	s_nop 0
	s_nop 0
	s_nop 0
	s_nop 0
	s_nop 0
	s_nop 0
	s_nop 0
	s_nop 0
	s_nop 0
	s_nop 0
	s_nop 0
	s_nop 0
	s_nop 0
	s_nop 0
	s_nop 0
	s_nop 0
	s_nop 0
	s_nop 0
	s_nop 0
	s_nop 0
	s_nop 0
	s_nop 0
	s_nop 0
	s_nop 0
	s_nop 0
	s_nop 0
	s_nop 0
	s_nop 0
	s_nop 0
	s_nop 0
	s_nop 0
	s_nop 0
	s_nop 0
	s_nop 0
	s_nop 0
	s_nop 0
	s_nop 0
	s_nop 0
	s_nop 0
	s_nop 0
	s_nop 0
	s_nop 0
	s_nop 0
	s_nop 0
	s_nop 0
	s_nop 0
	s_nop 0
	s_nop 0
	s_nop 0
	s_nop 0
	s_nop 0
	s_nop 0
	s_nop 0
	s_nop 0
	s_nop 0
	s_nop 0
	s_nop 0
	s_nop 0
	s_nop 0
	s_nop 0
	s_nop 0
	s_nop 0
	s_nop 0
	s_nop 0
	s_nop 0
	s_nop 0
	s_nop 0
	s_nop 0
	s_nop 0
	s_nop 0
	s_nop 0
	s_nop 0
	s_nop 0
	s_nop 0
	s_nop 0
	s_nop 0
	s_nop 0
	s_nop 0
	s_nop 0
	s_nop 0
	s_nop 0
	s_nop 0
	s_nop 0
	s_nop 0
	s_nop 0
	s_nop 0
	s_nop 0
	s_nop 0
	s_nop 0
	s_nop 0
	s_nop 0
	s_nop 0
	s_nop 0
	s_nop 0
	s_nop 0
	s_nop 0
	s_nop 0
	s_nop 0
	s_nop 0
	s_nop 0
	s_nop 0
	s_nop 0
	s_nop 0
	s_nop 0
	s_nop 0
	s_nop 0
	s_nop 0
	s_nop 0
	s_nop 0
	s_nop 0
	s_nop 0
	s_nop 0
	s_nop 0
	s_nop 0
	s_nop 0
	s_nop 0
	s_nop 0
	s_nop 0
	s_nop 0
	s_nop 0
	s_nop 0
	s_nop 0
	s_nop 0
	s_nop 0
	s_nop 0
	s_nop 0
	s_nop 0
	s_nop 0
	s_nop 0
	s_nop 0
	s_nop 0
	s_nop 0
	s_nop 0
	s_nop 0
	s_nop 0
	s_nop 0
	s_nop 0
	s_nop 0
	s_nop 0
	s_nop 0
	s_nop 0
	s_nop 0
	s_nop 0
	s_nop 0
	s_nop 0
	s_nop 0
	s_nop 0
	s_nop 0
	s_nop 0
	s_nop 0
	s_nop 0
	s_nop 0
	s_nop 0
	s_nop 0
	s_nop 0
	s_nop 0
	s_nop 0
	s_nop 0
	s_nop 0
	s_nop 0
	s_nop 0
	s_nop 0
	s_nop 0
	s_nop 0
	s_nop 0
	s_nop 0
	s_nop 0
	s_nop 0
	s_nop 0
	s_nop 0
	s_nop 0
	s_nop 0
	s_nop 0
	s_nop 0
	s_nop 0
	s_nop 0
	s_nop 0
	s_nop 0
	s_nop 0
	s_nop 0
	s_nop 0
	s_nop 0
	s_nop 0
	s_nop 0
	s_nop 0
	s_nop 0
	s_nop 0
.LBB0_622:
	s_branch .LBB0_369
